# block prefetch loads use scalar base plus one 32-bit per-thread offset (one VALU instead of five per block)
# speedup vs baseline: 1.0105x; 1.0002x over previous
; #define LAS __attribute__((address_space(3)))
; template <int MODE  > ...
;     ...
;         const bool has_next = rem != 0ull; int jn = 0;
;         if (has_next) { jn = 63 - __builtin_clzll(rem); rem &= ~(1ull << jn);
;             kreg = *(const u32x4*)(Kg + (size_t)(64 * jn + skey) * 128 + schunk * 8);
;             if (NEEDV) vreg = *(const u32x4*)(Vg + (size_t)(64 * jn + skey) * 128 + schunk * 8); }
;     ...
;             const LAS bf16_t* kb = (const LAS bf16_t*)(lds + A_KBUF) + cur * 64 * KPITCH;
;             constexpr int STEP = CMPM ? 16 : 1;
;             const int Bint = CMPM ? (1024 * j + 31 - t + 64 * h) : (64 * j - t + 4 * h);
;             const float sl = slope2 * (float)STEP;
;             const float mref = st.m; const bool fresh = !(mref > -1e28f);
;             const float mest = fresh ? 0.f : mref;
;             const float basef = selbit ? (slope2 * (float)Bint - mest) : -1e30f;
;             int ptype;
;             if (MODE == 1) ptype = (j == cblk) ? 1 : 0;
;             else if (MODE == 2) ptype = (j == cblk) ? 1 : ((j == cblk - 8) ? 2 : 0);
;             else ptype = (64 * j + 63 <= 4 * cblk - 2) ? 0 : 1;
;             f32x16 s0, s1;
;             { const float sl2 = sl + sl, sl3 = sl2 + sl;
; #pragma unroll
;               for (int g8 = 0; g8 < 4; ++g8) {
;                   const float b0 = __builtin_fmaf(sl, (float)(8 * g8), basef), b1 = __builtin_fmaf(sl, (float)(8 * g8 + 32), basef);
;                   s0[4 * g8] = b0; s0[4 * g8 + 1] = b0 + sl; s0[4 * g8 + 2] = b0 + sl2; s0[4 * g8 + 3] = b0 + sl3;
;                   s1[4 * g8] = b1; s1[4 * g8 + 1] = b1 + sl; s1[4 * g8 + 2] = b1 + sl2; s1[4 * g8 + 3] = b1 + sl3;
;               } }
;             if (ptype == 1) {
;                 const float thr = 0.5f * slope2 - mest;
; #pragma unroll
;                 for (int i = 0; i < 16; ++i) { s0[i] = (s0[i] < thr) ? s0[i] : -1e30f; s1[i] = (s1[i] < thr) ? s1[i] : -1e30f; }
.Lm0_pre_w:
	s_waitcnt lgkmcnt(0)
	ds_write_b128 v214, v[160:163]
	ds_write_b128 v215, v[164:167] offset:18432
	s_waitcnt lgkmcnt(0)
	s_barrier
	v_mov_b32_e32 v224, 0
	v_mov_b32_e32 v225, v190
	v_mov_b32_e32 v252, v191
	v_mov_b32_e32 v253, v187
	v_readfirstlane_b32 s24, v192
	v_readfirstlane_b32 s25, v193
	v_readfirstlane_b32 s34, v194
	v_readfirstlane_b32 s35, v195
	v_lshlrev_b32_e32 v254, 4, v178
	v_and_b32_e32 v254, 0x70, v254
	v_lshl_or_b32 v254, v211, 8, v254
.LBB0_146:
	s_mov_b32 s21, 0
	s_cmp_eq_u64 s[22:23], 0
	s_cbranch_scc1 .Lm00_noload
	s_flbit_i32_b64 s91, s[22:23]
	s_xor_b32 s91, s91, 63
	s_lshl_b64 vcc, 1, s91
	s_andn2_b64 s[22:23], s[22:23], vcc
	s_mov_b32 s21, 1
	v_lshl_add_u32 v2, s91, 14, v254
	global_load_dwordx4 v[160:163], v2, s[24:25]
	global_load_dwordx4 v[164:167], v2, s[34:35]
.Lm00_noload:
.Lm0_body0:
	ds_read_b128 v[80:83], v216
	ds_read_b128 v[84:87], v216 offset:4608
	ds_read_b128 v[88:91], v216 offset:32
	ds_read_b128 v[92:95], v216 offset:4640
	ds_read_b128 v[96:99], v216 offset:64
	ds_read_b128 v[100:103], v216 offset:4672
	ds_read_b128 v[104:107], v216 offset:96
	ds_read_b128 v[108:111], v216 offset:4704
	v_lshl_add_u32 v1, s90, 10, v217
	v_cvt_f32_i32_e32 v48, v1
	v_cmp_nlt_f32_e64 s[14:15], s71, v219
	s_lshl_b32 s17, s90, 6
	s_or_b32 s17, s17, 63
	s_cmp_le_i32 s17, s69
	v_cndmask_b32_e64 v1, v219, 0, s[14:15]
	v_fma_f32 v60, v186, v48, -v1
	v_fma_f32 v64, 0, v190, v60
	v_fmamk_f32 v68, v190, 0x41000000, v60
	v_fmamk_f32 v72, v190, 0x41800000, v60
	v_fmamk_f32 v76, v190, 0x41c00000, v60
	v_fmamk_f32 v48, v190, 0x42000000, v60
	v_fmamk_f32 v52, v190, 0x42200000, v60
	v_fmamk_f32 v56, v190, 0x42400000, v60
	v_fmac_f32_e32 v60, 0x42600000, v190
	v_pk_add_f32 v[66:67], v[252:253], v[64:65] op_sel_hi:[1,0]
	v_pk_add_f32 v[64:65], v[224:225], v[64:65] op_sel_hi:[1,0]
	v_pk_add_f32 v[70:71], v[252:253], v[68:69] op_sel_hi:[1,0]
	v_pk_add_f32 v[68:69], v[224:225], v[68:69] op_sel_hi:[1,0]
	v_pk_add_f32 v[74:75], v[252:253], v[72:73] op_sel_hi:[1,0]
	v_pk_add_f32 v[72:73], v[224:225], v[72:73] op_sel_hi:[1,0]
	v_pk_add_f32 v[78:79], v[252:253], v[76:77] op_sel_hi:[1,0]
	v_pk_add_f32 v[76:77], v[224:225], v[76:77] op_sel_hi:[1,0]
	v_pk_add_f32 v[50:51], v[252:253], v[48:49] op_sel_hi:[1,0]
	v_pk_add_f32 v[48:49], v[224:225], v[48:49] op_sel_hi:[1,0]
	v_pk_add_f32 v[54:55], v[252:253], v[52:53] op_sel_hi:[1,0]
	v_pk_add_f32 v[52:53], v[224:225], v[52:53] op_sel_hi:[1,0]
	v_pk_add_f32 v[58:59], v[252:253], v[56:57] op_sel_hi:[1,0]
	v_pk_add_f32 v[56:57], v[224:225], v[56:57] op_sel_hi:[1,0]
	v_pk_add_f32 v[62:63], v[252:253], v[60:61] op_sel_hi:[1,0]
	v_pk_add_f32 v[60:61], v[224:225], v[60:61] op_sel_hi:[1,0]
	s_cbranch_scc1 .Lm00_qk
	v_sub_f32_e32 v235, v189, v1
	v_cmp_lt_f32_e32 vcc, v64, v235
	s_nop 1
	v_cndmask_b32_e32 v64, v241, v64, vcc
	v_cmp_lt_f32_e32 vcc, v65, v235
	s_nop 1
	v_cndmask_b32_e32 v65, v241, v65, vcc
	v_cmp_lt_f32_e32 vcc, v66, v235
	s_nop 1
	v_cndmask_b32_e32 v66, v241, v66, vcc
	v_cmp_lt_f32_e32 vcc, v67, v235
	s_nop 1
	v_cndmask_b32_e32 v67, v241, v67, vcc
	v_cmp_lt_f32_e32 vcc, v68, v235
	s_nop 1
	v_cndmask_b32_e32 v68, v241, v68, vcc
	v_cmp_lt_f32_e32 vcc, v69, v235
	s_nop 1
	v_cndmask_b32_e32 v69, v241, v69, vcc
	v_cmp_lt_f32_e32 vcc, v70, v235
	s_nop 1
	v_cndmask_b32_e32 v70, v241, v70, vcc
	v_cmp_lt_f32_e32 vcc, v71, v235
	s_nop 1
	v_cndmask_b32_e32 v71, v241, v71, vcc
	v_cmp_lt_f32_e32 vcc, v72, v235
	s_nop 1
	v_cndmask_b32_e32 v72, v241, v72, vcc
	v_cmp_lt_f32_e32 vcc, v73, v235
	s_nop 1
	v_cndmask_b32_e32 v73, v241, v73, vcc
	v_cmp_lt_f32_e32 vcc, v74, v235
	s_nop 1
	v_cndmask_b32_e32 v74, v241, v74, vcc
	v_cmp_lt_f32_e32 vcc, v75, v235
	s_nop 1
	v_cndmask_b32_e32 v75, v241, v75, vcc
	v_cmp_lt_f32_e32 vcc, v76, v235
	s_nop 1
	v_cndmask_b32_e32 v76, v241, v76, vcc
	v_cmp_lt_f32_e32 vcc, v77, v235
	s_nop 1
	v_cndmask_b32_e32 v77, v241, v77, vcc
	v_cmp_lt_f32_e32 vcc, v78, v235
	s_nop 1
	v_cndmask_b32_e32 v78, v241, v78, vcc
	v_cmp_lt_f32_e32 vcc, v79, v235
	s_nop 1
	v_cndmask_b32_e32 v79, v241, v79, vcc
	v_cmp_lt_f32_e32 vcc, v48, v235
	s_nop 1
	v_cndmask_b32_e32 v48, v241, v48, vcc
	v_cmp_lt_f32_e32 vcc, v49, v235
	s_nop 1
	v_cndmask_b32_e32 v49, v241, v49, vcc
	v_cmp_lt_f32_e32 vcc, v50, v235
	s_nop 1
	v_cndmask_b32_e32 v50, v241, v50, vcc
	v_cmp_lt_f32_e32 vcc, v51, v235
	s_nop 1
	v_cndmask_b32_e32 v51, v241, v51, vcc
	v_cmp_lt_f32_e32 vcc, v52, v235
	s_nop 1
	v_cndmask_b32_e32 v52, v241, v52, vcc
	v_cmp_lt_f32_e32 vcc, v53, v235
	s_nop 1
	v_cndmask_b32_e32 v53, v241, v53, vcc
	v_cmp_lt_f32_e32 vcc, v54, v235
	s_nop 1
	v_cndmask_b32_e32 v54, v241, v54, vcc
	v_cmp_lt_f32_e32 vcc, v55, v235
	s_nop 1
	v_cndmask_b32_e32 v55, v241, v55, vcc
	v_cmp_lt_f32_e32 vcc, v56, v235
	s_nop 1
	v_cndmask_b32_e32 v56, v241, v56, vcc
	v_cmp_lt_f32_e32 vcc, v57, v235
	s_nop 1
	v_cndmask_b32_e32 v57, v241, v57, vcc
	v_cmp_lt_f32_e32 vcc, v58, v235
	s_nop 1
	v_cndmask_b32_e32 v58, v241, v58, vcc
	v_cmp_lt_f32_e32 vcc, v59, v235
	s_nop 1
	v_cndmask_b32_e32 v59, v241, v59, vcc
	v_cmp_lt_f32_e32 vcc, v60, v235
	s_nop 1
	v_cndmask_b32_e32 v60, v241, v60, vcc
	v_cmp_lt_f32_e32 vcc, v61, v235
	s_nop 1
	v_cndmask_b32_e32 v61, v241, v61, vcc
	v_cmp_lt_f32_e32 vcc, v62, v235
	s_nop 1
	v_cndmask_b32_e32 v62, v241, v62, vcc
	v_cmp_lt_f32_e32 vcc, v63, v235
	s_nop 1
	v_cndmask_b32_e32 v63, v241, v63, vcc

; #define LAS __attribute__((address_space(3)))
; template <int MODE  > ...
;     ...
;         const bool has_next = rem != 0ull; int jn = 0;
;         if (has_next) { jn = 63 - __builtin_clzll(rem); rem &= ~(1ull << jn);
;             kreg = *(const u32x4*)(Kg + (size_t)(64 * jn + skey) * 128 + schunk * 8);
;             if (NEEDV) vreg = *(const u32x4*)(Vg + (size_t)(64 * jn + skey) * 128 + schunk * 8); }
;     ...
;             const LAS bf16_t* kb = (const LAS bf16_t*)(lds + A_KBUF) + cur * 64 * KPITCH;
;             constexpr int STEP = CMPM ? 16 : 1;
;             const int Bint = CMPM ? (1024 * j + 31 - t + 64 * h) : (64 * j - t + 4 * h);
;             const float sl = slope2 * (float)STEP;
;             const float mref = st.m; const bool fresh = !(mref > -1e28f);
;             const float mest = fresh ? 0.f : mref;
;             const float basef = selbit ? (slope2 * (float)Bint - mest) : -1e30f;
;             int ptype;
;             if (MODE == 1) ptype = (j == cblk) ? 1 : 0;
;             else if (MODE == 2) ptype = (j == cblk) ? 1 : ((j == cblk - 8) ? 2 : 0);
;             else ptype = (64 * j + 63 <= 4 * cblk - 2) ? 0 : 1;
;             f32x16 s0, s1;
;             { const float sl2 = sl + sl, sl3 = sl2 + sl;
; #pragma unroll
;               for (int g8 = 0; g8 < 4; ++g8) {
;                   const float b0 = __builtin_fmaf(sl, (float)(8 * g8), basef), b1 = __builtin_fmaf(sl, (float)(8 * g8 + 32), basef);
;                   s0[4 * g8] = b0; s0[4 * g8 + 1] = b0 + sl; s0[4 * g8 + 2] = b0 + sl2; s0[4 * g8 + 3] = b0 + sl3;
;                   s1[4 * g8] = b1; s1[4 * g8 + 1] = b1 + sl; s1[4 * g8 + 2] = b1 + sl2; s1[4 * g8 + 3] = b1 + sl3;
;               } }
;             if (ptype == 1) {
;                 const float thr = 0.5f * slope2 - mest;
; #pragma unroll
;                 for (int i = 0; i < 16; ++i) { s0[i] = (s0[i] < thr) ? s0[i] : -1e30f; s1[i] = (s1[i] < thr) ? s1[i] : -1e30f; }
.Lm0_loop1:
	s_mov_b32 s21, 0
	s_cmp_eq_u64 s[22:23], 0
	s_cbranch_scc1 .Lm01_noload
	s_flbit_i32_b64 s91, s[22:23]
	s_xor_b32 s91, s91, 63
	s_lshl_b64 vcc, 1, s91
	s_andn2_b64 s[22:23], s[22:23], vcc
	s_mov_b32 s21, 1
	v_lshl_add_u32 v2, s91, 14, v254
	global_load_dwordx4 v[226:229], v2, s[24:25]
	global_load_dwordx4 v[230:233], v2, s[34:35]
.Lm01_noload:
.Lm0_body1:
	ds_read_b128 v[80:83], v216 offset:9216
	ds_read_b128 v[84:87], v216 offset:13824
	ds_read_b128 v[88:91], v216 offset:9248
	ds_read_b128 v[92:95], v216 offset:13856
	ds_read_b128 v[96:99], v216 offset:9280
	ds_read_b128 v[100:103], v216 offset:13888
	ds_read_b128 v[104:107], v216 offset:9312
	ds_read_b128 v[108:111], v216 offset:13920
	v_lshl_add_u32 v1, s90, 10, v217
	v_cvt_f32_i32_e32 v48, v1
	v_cmp_nlt_f32_e64 s[14:15], s71, v219
	s_lshl_b32 s17, s90, 6
	s_or_b32 s17, s17, 63
	s_cmp_le_i32 s17, s69
	v_cndmask_b32_e64 v1, v219, 0, s[14:15]
	v_fma_f32 v60, v186, v48, -v1
	v_fma_f32 v64, 0, v190, v60
	v_fmamk_f32 v68, v190, 0x41000000, v60
	v_fmamk_f32 v72, v190, 0x41800000, v60
	v_fmamk_f32 v76, v190, 0x41c00000, v60
	v_fmamk_f32 v48, v190, 0x42000000, v60
	v_fmamk_f32 v52, v190, 0x42200000, v60
	v_fmamk_f32 v56, v190, 0x42400000, v60
	v_fmac_f32_e32 v60, 0x42600000, v190
	v_pk_add_f32 v[66:67], v[252:253], v[64:65] op_sel_hi:[1,0]
	v_pk_add_f32 v[64:65], v[224:225], v[64:65] op_sel_hi:[1,0]
	v_pk_add_f32 v[70:71], v[252:253], v[68:69] op_sel_hi:[1,0]
	v_pk_add_f32 v[68:69], v[224:225], v[68:69] op_sel_hi:[1,0]
	v_pk_add_f32 v[74:75], v[252:253], v[72:73] op_sel_hi:[1,0]
	v_pk_add_f32 v[72:73], v[224:225], v[72:73] op_sel_hi:[1,0]
	v_pk_add_f32 v[78:79], v[252:253], v[76:77] op_sel_hi:[1,0]
	v_pk_add_f32 v[76:77], v[224:225], v[76:77] op_sel_hi:[1,0]
	v_pk_add_f32 v[50:51], v[252:253], v[48:49] op_sel_hi:[1,0]
	v_pk_add_f32 v[48:49], v[224:225], v[48:49] op_sel_hi:[1,0]
	v_pk_add_f32 v[54:55], v[252:253], v[52:53] op_sel_hi:[1,0]
	v_pk_add_f32 v[52:53], v[224:225], v[52:53] op_sel_hi:[1,0]
	v_pk_add_f32 v[58:59], v[252:253], v[56:57] op_sel_hi:[1,0]
	v_pk_add_f32 v[56:57], v[224:225], v[56:57] op_sel_hi:[1,0]
	v_pk_add_f32 v[62:63], v[252:253], v[60:61] op_sel_hi:[1,0]
	v_pk_add_f32 v[60:61], v[224:225], v[60:61] op_sel_hi:[1,0]
	s_cbranch_scc1 .Lm01_qk
	v_sub_f32_e32 v235, v189, v1
	v_cmp_lt_f32_e32 vcc, v64, v235
	s_nop 1
	v_cndmask_b32_e32 v64, v241, v64, vcc
	v_cmp_lt_f32_e32 vcc, v65, v235
	s_nop 1
	v_cndmask_b32_e32 v65, v241, v65, vcc
	v_cmp_lt_f32_e32 vcc, v66, v235
	s_nop 1
	v_cndmask_b32_e32 v66, v241, v66, vcc
	v_cmp_lt_f32_e32 vcc, v67, v235
	s_nop 1
	v_cndmask_b32_e32 v67, v241, v67, vcc
	v_cmp_lt_f32_e32 vcc, v68, v235
	s_nop 1
	v_cndmask_b32_e32 v68, v241, v68, vcc
	v_cmp_lt_f32_e32 vcc, v69, v235
	s_nop 1
	v_cndmask_b32_e32 v69, v241, v69, vcc
	v_cmp_lt_f32_e32 vcc, v70, v235
	s_nop 1
	v_cndmask_b32_e32 v70, v241, v70, vcc
	v_cmp_lt_f32_e32 vcc, v71, v235
	s_nop 1
	v_cndmask_b32_e32 v71, v241, v71, vcc
	v_cmp_lt_f32_e32 vcc, v72, v235
	s_nop 1
	v_cndmask_b32_e32 v72, v241, v72, vcc
	v_cmp_lt_f32_e32 vcc, v73, v235
	s_nop 1
	v_cndmask_b32_e32 v73, v241, v73, vcc
	v_cmp_lt_f32_e32 vcc, v74, v235
	s_nop 1
	v_cndmask_b32_e32 v74, v241, v74, vcc
	v_cmp_lt_f32_e32 vcc, v75, v235
	s_nop 1
	v_cndmask_b32_e32 v75, v241, v75, vcc
	v_cmp_lt_f32_e32 vcc, v76, v235
	s_nop 1
	v_cndmask_b32_e32 v76, v241, v76, vcc
	v_cmp_lt_f32_e32 vcc, v77, v235
	s_nop 1
	v_cndmask_b32_e32 v77, v241, v77, vcc
	v_cmp_lt_f32_e32 vcc, v78, v235
	s_nop 1
	v_cndmask_b32_e32 v78, v241, v78, vcc
	v_cmp_lt_f32_e32 vcc, v79, v235
	s_nop 1
	v_cndmask_b32_e32 v79, v241, v79, vcc
	v_cmp_lt_f32_e32 vcc, v48, v235
	s_nop 1
	v_cndmask_b32_e32 v48, v241, v48, vcc
	v_cmp_lt_f32_e32 vcc, v49, v235
	s_nop 1
	v_cndmask_b32_e32 v49, v241, v49, vcc
	v_cmp_lt_f32_e32 vcc, v50, v235
	s_nop 1
	v_cndmask_b32_e32 v50, v241, v50, vcc
	v_cmp_lt_f32_e32 vcc, v51, v235
	s_nop 1
	v_cndmask_b32_e32 v51, v241, v51, vcc
	v_cmp_lt_f32_e32 vcc, v52, v235
	s_nop 1
	v_cndmask_b32_e32 v52, v241, v52, vcc
	v_cmp_lt_f32_e32 vcc, v53, v235
	s_nop 1
	v_cndmask_b32_e32 v53, v241, v53, vcc
	v_cmp_lt_f32_e32 vcc, v54, v235
	s_nop 1
	v_cndmask_b32_e32 v54, v241, v54, vcc
	v_cmp_lt_f32_e32 vcc, v55, v235
	s_nop 1
	v_cndmask_b32_e32 v55, v241, v55, vcc
	v_cmp_lt_f32_e32 vcc, v56, v235
	s_nop 1
	v_cndmask_b32_e32 v56, v241, v56, vcc
	v_cmp_lt_f32_e32 vcc, v57, v235
	s_nop 1
	v_cndmask_b32_e32 v57, v241, v57, vcc
	v_cmp_lt_f32_e32 vcc, v58, v235
	s_nop 1
	v_cndmask_b32_e32 v58, v241, v58, vcc
	v_cmp_lt_f32_e32 vcc, v59, v235
	s_nop 1
	v_cndmask_b32_e32 v59, v241, v59, vcc
	v_cmp_lt_f32_e32 vcc, v60, v235
	s_nop 1
	v_cndmask_b32_e32 v60, v241, v60, vcc
	v_cmp_lt_f32_e32 vcc, v61, v235
	s_nop 1
	v_cndmask_b32_e32 v61, v241, v61, vcc
	v_cmp_lt_f32_e32 vcc, v62, v235
	s_nop 1
	v_cndmask_b32_e32 v62, v241, v62, vcc
	v_cmp_lt_f32_e32 vcc, v63, v235
	s_nop 1
	v_cndmask_b32_e32 v63, v241, v63, vcc

; #define LAS __attribute__((address_space(3)))
; template <int MODE  > ...
;     ...
;     {
;         LAS bf16_t* kb = (LAS bf16_t*)(lds + A_KBUF) + cur * 64 * KPITCH;
;         *(LAS u32x4*)(kb + skey * KPITCH + schunk * 8) = kreg;
;         if (NEEDV) { LAS bf16_t* vb = (LAS bf16_t*)(lds + A_VBUF) + cur * 64 * VPITCH;
;             *(LAS u32x4*)(vb + skey * VPITCH + schunk * 8) = vreg; }
;     }
;     __syncthreads();
;     for (;;) {
;         const bool has_next = rem != 0ull; int jn = 0;
;         if (has_next) { jn = 63 - __builtin_clzll(rem); rem &= ~(1ull << jn);
;             kreg = *(const u32x4*)(Kg + (size_t)(64 * jn + skey) * 128 + schunk * 8);
;             if (NEEDV) vreg = *(const u32x4*)(Vg + (size_t)(64 * jn + skey) * 128 + schunk * 8); }
;         const bool selbit = (MODE == 1) ? (((selmask >> j) & 1ull) != 0ull) : true;
;         bool active = true;
;         if (MODE == 1) active = __builtin_amdgcn_ballot_w64(selbit) != 0ull;
;         if (active) {
;             const LAS bf16_t* kb = (const LAS bf16_t*)(lds + A_KBUF) + cur * 64 * KPITCH;
;             constexpr int STEP = CMPM ? 16 : 1;
;             const int Bint = CMPM ? (1024 * j + 31 - t + 64 * h) : (64 * j - t + 4 * h);
;             const float sl = slope2 * (float)STEP;
;             const float mref = st.m; const bool fresh = !(mref > -1e28f);
;             const float mest = fresh ? 0.f : mref;
;             const float basef = selbit ? (slope2 * (float)Bint - mest) : -1e30f;
;             int ptype;
;             if (MODE == 1) ptype = (j == cblk) ? 1 : 0;
;             else if (MODE == 2) ptype = (j == cblk) ? 1 : ((j == cblk - 8) ? 2 : 0);
;             else ptype = (64 * j + 63 <= 4 * cblk - 2) ? 0 : 1;
;             f32x16 s0, s1;
;             { const float sl2 = sl + sl, sl3 = sl2 + sl;
; #pragma unroll
;               for (int g8 = 0; g8 < 4; ++g8) {
;                   const float b0 = __builtin_fmaf(sl, (float)(8 * g8), basef), b1 = __builtin_fmaf(sl, (float)(8 * g8 + 32), basef);
;                   s0[4 * g8] = b0; s0[4 * g8 + 1] = b0 + sl; s0[4 * g8 + 2] = b0 + sl2; s0[4 * g8 + 3] = b0 + sl3;
;                   s1[4 * g8] = b1; s1[4 * g8 + 1] = b1 + sl; s1[4 * g8 + 2] = b1 + sl2; s1[4 * g8 + 3] = b1 + sl3;
;               } }
;             if (ptype == 1) {
;                 const float thr = 0.5f * slope2 - mest;
; #pragma unroll
.Lm1_pre_w:
	s_waitcnt lgkmcnt(0)
	ds_write_b128 v166, v[220:223]
	ds_write_b128 v167, v[248:251] offset:18432
	s_waitcnt lgkmcnt(0)
	s_barrier
	s_lshl_b32 s4, s22, 1
	s_add_u32 s14, s49, s4
	s_addc_u32 s15, s82, 0
	s_add_u32 s4, s47, s4
	s_addc_u32 s5, s48, 0
	v_lshl_add_u32 v2, s83, 6, v164
	v_ashrrev_i32_e32 v3, 31, v2
	v_lshlrev_b64 v[2:3], 8, v[2:3]
	v_lshlrev_b32_e32 v4, 4, v178
	v_and_b32_e32 v4, 0x70, v4
	v_or_b32_e32 v2, v2, v4
	v_lshl_add_u64 v[4:5], s[14:15], 0, v[2:3]
	global_load_dwordx4 v[220:223], v[4:5], off
	v_lshl_add_u64 v[4:5], s[4:5], 0, v[2:3]
	global_load_dwordx4 v[248:251], v[4:5], off
	v_mov_b32_e32 v224, 0
	v_mov_b32_e32 v225, v186
	v_mov_b32_e32 v252, v187
	v_mov_b32_e32 v253, v163
	v_readfirstlane_b32 s24, v160
	v_readfirstlane_b32 s25, v161
	v_readfirstlane_b32 s34, v142
	v_readfirstlane_b32 s35, v143
	v_lshlrev_b32_e32 v254, 4, v178
	v_and_b32_e32 v254, 0x70, v254
	v_lshl_or_b32 v254, v164, 8, v254
.LBB0_248:
	s_mov_b32 s21, 0
	s_cmp_eq_u64 s[18:19], 0
	s_cbranch_scc1 .Lm10_noload
	s_flbit_i32_b64 s4, s[18:19]
	s_xor_b32 s4, s4, 63
	s_lshl_b64 vcc, 1, s4
	s_andn2_b64 s[18:19], s[18:19], vcc
	s_mov_b32 s21, 1
	v_lshl_add_u32 v2, s4, 14, v254
	global_load_dwordx4 v[130:133], v2, s[24:25]
	global_load_dwordx4 v[134:137], v2, s[34:35]
.Lm10_noload:
.Lm1_body0:
	v_lshrrev_b64 v[2:3], s68, v[140:141]
	v_and_b32_e32 v1, 1, v2
	v_cmp_eq_u32_e64 s[16:17], 1, v1
	v_cmp_ne_u32_e32 vcc, 0, v1
	s_cbranch_vccz .Lm1_stage0
	ds_read_b128 v[66:69], v191
	ds_read_b128 v[70:73], v191 offset:4608
	ds_read_b128 v[74:77], v191 offset:32
	ds_read_b128 v[78:81], v191 offset:4640
	ds_read_b128 v[82:85], v191 offset:64
	ds_read_b128 v[86:89], v191 offset:4672
	ds_read_b128 v[90:93], v191 offset:96
	ds_read_b128 v[94:97], v191 offset:4704
	v_lshl_add_u32 v1, s68, 6, v190
	v_cvt_f32_i32_e32 v2, v1
	v_cmp_nlt_f32_e64 s[14:15], s71, v194
	s_cmp_lg_u32 s68, s83
	s_nop 0
	v_cndmask_b32_e64 v1, v194, 0, s[14:15]
	v_fma_f32 v2, v186, v2, -v1
	v_cndmask_b32_e64 v14, v241, v2, s[16:17]
	v_fma_f32 v50, 0, v186, v14
	v_fmamk_f32 v54, v186, 0x41000000, v14
	v_fmamk_f32 v58, v186, 0x41800000, v14
	v_fmamk_f32 v62, v186, 0x41c00000, v14
	v_fmamk_f32 v2, v186, 0x42000000, v14
	v_fmamk_f32 v6, v186, 0x42200000, v14
	v_fmamk_f32 v10, v186, 0x42400000, v14
	v_fmac_f32_e32 v14, 0x42600000, v186
	v_pk_add_f32 v[52:53], v[252:253], v[50:51] op_sel_hi:[1,0]
	v_pk_add_f32 v[50:51], v[224:225], v[50:51] op_sel_hi:[1,0]
	v_pk_add_f32 v[56:57], v[252:253], v[54:55] op_sel_hi:[1,0]
	v_pk_add_f32 v[54:55], v[224:225], v[54:55] op_sel_hi:[1,0]
	v_pk_add_f32 v[60:61], v[252:253], v[58:59] op_sel_hi:[1,0]
	v_pk_add_f32 v[58:59], v[224:225], v[58:59] op_sel_hi:[1,0]
	v_pk_add_f32 v[64:65], v[252:253], v[62:63] op_sel_hi:[1,0]
	v_pk_add_f32 v[62:63], v[224:225], v[62:63] op_sel_hi:[1,0]
	v_pk_add_f32 v[4:5], v[252:253], v[2:3] op_sel_hi:[1,0]
	v_pk_add_f32 v[2:3], v[224:225], v[2:3] op_sel_hi:[1,0]
	v_pk_add_f32 v[8:9], v[252:253], v[6:7] op_sel_hi:[1,0]
	v_pk_add_f32 v[6:7], v[224:225], v[6:7] op_sel_hi:[1,0]
	v_pk_add_f32 v[12:13], v[252:253], v[10:11] op_sel_hi:[1,0]
	v_pk_add_f32 v[10:11], v[224:225], v[10:11] op_sel_hi:[1,0]
	v_pk_add_f32 v[16:17], v[252:253], v[14:15] op_sel_hi:[1,0]
	v_pk_add_f32 v[14:15], v[224:225], v[14:15] op_sel_hi:[1,0]
	s_cbranch_scc1 .Lm10_qk
	v_sub_f32_e32 v235, v189, v1
	v_cmp_lt_f32_e32 vcc, v50, v235
	s_nop 1
	v_cndmask_b32_e32 v50, v241, v50, vcc
	v_cmp_lt_f32_e32 vcc, v51, v235
	s_nop 1
	v_cndmask_b32_e32 v51, v241, v51, vcc
	v_cmp_lt_f32_e32 vcc, v52, v235
	s_nop 1
	v_cndmask_b32_e32 v52, v241, v52, vcc
	v_cmp_lt_f32_e32 vcc, v53, v235
	s_nop 1
	v_cndmask_b32_e32 v53, v241, v53, vcc
	v_cmp_lt_f32_e32 vcc, v54, v235
	s_nop 1
	v_cndmask_b32_e32 v54, v241, v54, vcc
	v_cmp_lt_f32_e32 vcc, v55, v235
	s_nop 1
	v_cndmask_b32_e32 v55, v241, v55, vcc
	v_cmp_lt_f32_e32 vcc, v56, v235
	s_nop 1
	v_cndmask_b32_e32 v56, v241, v56, vcc
	v_cmp_lt_f32_e32 vcc, v57, v235
	s_nop 1
	v_cndmask_b32_e32 v57, v241, v57, vcc
	v_cmp_lt_f32_e32 vcc, v58, v235
	s_nop 1
	v_cndmask_b32_e32 v58, v241, v58, vcc
	v_cmp_lt_f32_e32 vcc, v59, v235
	s_nop 1
	v_cndmask_b32_e32 v59, v241, v59, vcc
	v_cmp_lt_f32_e32 vcc, v60, v235
	s_nop 1
	v_cndmask_b32_e32 v60, v241, v60, vcc
	v_cmp_lt_f32_e32 vcc, v61, v235
	s_nop 1
	v_cndmask_b32_e32 v61, v241, v61, vcc
	v_cmp_lt_f32_e32 vcc, v62, v235
	s_nop 1
	v_cndmask_b32_e32 v62, v241, v62, vcc
	v_cmp_lt_f32_e32 vcc, v63, v235
	s_nop 1
	v_cndmask_b32_e32 v63, v241, v63, vcc
	v_cmp_lt_f32_e32 vcc, v64, v235
	s_nop 1
	v_cndmask_b32_e32 v64, v241, v64, vcc
	v_cmp_lt_f32_e32 vcc, v65, v235
	s_nop 1
	v_cndmask_b32_e32 v65, v241, v65, vcc
	v_cmp_lt_f32_e32 vcc, v2, v235
	s_nop 1
	v_cndmask_b32_e32 v2, v241, v2, vcc
	v_cmp_lt_f32_e32 vcc, v3, v235
	s_nop 1
	v_cndmask_b32_e32 v3, v241, v3, vcc
	v_cmp_lt_f32_e32 vcc, v4, v235
	s_nop 1
	v_cndmask_b32_e32 v4, v241, v4, vcc
	v_cmp_lt_f32_e32 vcc, v5, v235
	s_nop 1
	v_cndmask_b32_e32 v5, v241, v5, vcc
	v_cmp_lt_f32_e32 vcc, v6, v235
	s_nop 1
	v_cndmask_b32_e32 v6, v241, v6, vcc
	v_cmp_lt_f32_e32 vcc, v7, v235
	s_nop 1
	v_cndmask_b32_e32 v7, v241, v7, vcc
	v_cmp_lt_f32_e32 vcc, v8, v235
	s_nop 1
	v_cndmask_b32_e32 v8, v241, v8, vcc
	v_cmp_lt_f32_e32 vcc, v9, v235
	s_nop 1
	v_cndmask_b32_e32 v9, v241, v9, vcc
	v_cmp_lt_f32_e32 vcc, v10, v235
	s_nop 1
	v_cndmask_b32_e32 v10, v241, v10, vcc
	v_cmp_lt_f32_e32 vcc, v11, v235
	s_nop 1
	v_cndmask_b32_e32 v11, v241, v11, vcc
	v_cmp_lt_f32_e32 vcc, v12, v235
	s_nop 1
	v_cndmask_b32_e32 v12, v241, v12, vcc
	v_cmp_lt_f32_e32 vcc, v13, v235
	s_nop 1
	v_cndmask_b32_e32 v13, v241, v13, vcc
	v_cmp_lt_f32_e32 vcc, v14, v235
	s_nop 1
	v_cndmask_b32_e32 v14, v241, v14, vcc
	v_cmp_lt_f32_e32 vcc, v15, v235
	s_nop 1
	v_cndmask_b32_e32 v15, v241, v15, vcc
	v_cmp_lt_f32_e32 vcc, v16, v235
	s_nop 1
	v_cndmask_b32_e32 v16, v241, v16, vcc
	v_cmp_lt_f32_e32 vcc, v17, v235
	s_nop 1
	v_cndmask_b32_e32 v17, v241, v17, vcc

; #define LAS __attribute__((address_space(3)))
; template <int MODE  > ...
;     ...
;         const bool has_next = rem != 0ull; int jn = 0;
;         if (has_next) { jn = 63 - __builtin_clzll(rem); rem &= ~(1ull << jn);
;             kreg = *(const u32x4*)(Kg + (size_t)(64 * jn + skey) * 128 + schunk * 8);
;             if (NEEDV) vreg = *(const u32x4*)(Vg + (size_t)(64 * jn + skey) * 128 + schunk * 8); }
;         const bool selbit = (MODE == 1) ? (((selmask >> j) & 1ull) != 0ull) : true;
;         bool active = true;
;         if (MODE == 1) active = __builtin_amdgcn_ballot_w64(selbit) != 0ull;
;         if (active) {
;             const LAS bf16_t* kb = (const LAS bf16_t*)(lds + A_KBUF) + cur * 64 * KPITCH;
;             constexpr int STEP = CMPM ? 16 : 1;
;             const int Bint = CMPM ? (1024 * j + 31 - t + 64 * h) : (64 * j - t + 4 * h);
;             const float sl = slope2 * (float)STEP;
;             const float mref = st.m; const bool fresh = !(mref > -1e28f);
;             const float mest = fresh ? 0.f : mref;
;             const float basef = selbit ? (slope2 * (float)Bint - mest) : -1e30f;
;             int ptype;
;             if (MODE == 1) ptype = (j == cblk) ? 1 : 0;
;             else if (MODE == 2) ptype = (j == cblk) ? 1 : ((j == cblk - 8) ? 2 : 0);
;             else ptype = (64 * j + 63 <= 4 * cblk - 2) ? 0 : 1;
;             f32x16 s0, s1;
;             { const float sl2 = sl + sl, sl3 = sl2 + sl;
; #pragma unroll
;               for (int g8 = 0; g8 < 4; ++g8) {
;                   const float b0 = __builtin_fmaf(sl, (float)(8 * g8), basef), b1 = __builtin_fmaf(sl, (float)(8 * g8 + 32), basef);
;                   s0[4 * g8] = b0; s0[4 * g8 + 1] = b0 + sl; s0[4 * g8 + 2] = b0 + sl2; s0[4 * g8 + 3] = b0 + sl3;
;                   s1[4 * g8] = b1; s1[4 * g8 + 1] = b1 + sl; s1[4 * g8 + 2] = b1 + sl2; s1[4 * g8 + 3] = b1 + sl3;
;               } }
;             if (ptype == 1) {
;                 const float thr = 0.5f * slope2 - mest;
; #pragma unroll
;                 for (int i = 0; i < 16; ++i) { s0[i] = (s0[i] < thr) ? s0[i] : -1e30f; s1[i] = (s1[i] < thr) ? s1[i] : -1e30f; }
.Lm1_loop1:
	s_mov_b32 s21, 0
	s_cmp_eq_u64 s[18:19], 0
	s_cbranch_scc1 .Lm11_noload
	s_flbit_i32_b64 s4, s[18:19]
	s_xor_b32 s4, s4, 63
	s_lshl_b64 vcc, 1, s4
	s_andn2_b64 s[18:19], s[18:19], vcc
	s_mov_b32 s21, 1
	v_lshl_add_u32 v2, s4, 14, v254
	global_load_dwordx4 v[226:229], v2, s[24:25]
	global_load_dwordx4 v[230:233], v2, s[34:35]
.Lm11_noload:
.Lm1_body1:
	v_lshrrev_b64 v[2:3], s68, v[140:141]
	v_and_b32_e32 v1, 1, v2
	v_cmp_eq_u32_e64 s[16:17], 1, v1
	v_cmp_ne_u32_e32 vcc, 0, v1
	s_cbranch_vccz .Lm1_stage1
	ds_read_b128 v[66:69], v191 offset:9216
	ds_read_b128 v[70:73], v191 offset:13824
	ds_read_b128 v[74:77], v191 offset:9248
	ds_read_b128 v[78:81], v191 offset:13856
	ds_read_b128 v[82:85], v191 offset:9280
	ds_read_b128 v[86:89], v191 offset:13888
	ds_read_b128 v[90:93], v191 offset:9312
	ds_read_b128 v[94:97], v191 offset:13920
	v_lshl_add_u32 v1, s68, 6, v190
	v_cvt_f32_i32_e32 v2, v1
	v_cmp_nlt_f32_e64 s[14:15], s71, v194
	s_cmp_lg_u32 s68, s83
	s_nop 0
	v_cndmask_b32_e64 v1, v194, 0, s[14:15]
	v_fma_f32 v2, v186, v2, -v1
	v_cndmask_b32_e64 v14, v241, v2, s[16:17]
	v_fma_f32 v50, 0, v186, v14
	v_fmamk_f32 v54, v186, 0x41000000, v14
	v_fmamk_f32 v58, v186, 0x41800000, v14
	v_fmamk_f32 v62, v186, 0x41c00000, v14
	v_fmamk_f32 v2, v186, 0x42000000, v14
	v_fmamk_f32 v6, v186, 0x42200000, v14
	v_fmamk_f32 v10, v186, 0x42400000, v14
	v_fmac_f32_e32 v14, 0x42600000, v186
	v_pk_add_f32 v[52:53], v[252:253], v[50:51] op_sel_hi:[1,0]
	v_pk_add_f32 v[50:51], v[224:225], v[50:51] op_sel_hi:[1,0]
	v_pk_add_f32 v[56:57], v[252:253], v[54:55] op_sel_hi:[1,0]
	v_pk_add_f32 v[54:55], v[224:225], v[54:55] op_sel_hi:[1,0]
	v_pk_add_f32 v[60:61], v[252:253], v[58:59] op_sel_hi:[1,0]
	v_pk_add_f32 v[58:59], v[224:225], v[58:59] op_sel_hi:[1,0]
	v_pk_add_f32 v[64:65], v[252:253], v[62:63] op_sel_hi:[1,0]
	v_pk_add_f32 v[62:63], v[224:225], v[62:63] op_sel_hi:[1,0]
	v_pk_add_f32 v[4:5], v[252:253], v[2:3] op_sel_hi:[1,0]
	v_pk_add_f32 v[2:3], v[224:225], v[2:3] op_sel_hi:[1,0]
	v_pk_add_f32 v[8:9], v[252:253], v[6:7] op_sel_hi:[1,0]
	v_pk_add_f32 v[6:7], v[224:225], v[6:7] op_sel_hi:[1,0]
	v_pk_add_f32 v[12:13], v[252:253], v[10:11] op_sel_hi:[1,0]
	v_pk_add_f32 v[10:11], v[224:225], v[10:11] op_sel_hi:[1,0]
	v_pk_add_f32 v[16:17], v[252:253], v[14:15] op_sel_hi:[1,0]
	v_pk_add_f32 v[14:15], v[224:225], v[14:15] op_sel_hi:[1,0]
	s_cbranch_scc1 .Lm11_qk
	v_sub_f32_e32 v235, v189, v1
	v_cmp_lt_f32_e32 vcc, v50, v235
	s_nop 1
	v_cndmask_b32_e32 v50, v241, v50, vcc
	v_cmp_lt_f32_e32 vcc, v51, v235
	s_nop 1
	v_cndmask_b32_e32 v51, v241, v51, vcc
	v_cmp_lt_f32_e32 vcc, v52, v235
	s_nop 1
	v_cndmask_b32_e32 v52, v241, v52, vcc
	v_cmp_lt_f32_e32 vcc, v53, v235
	s_nop 1
	v_cndmask_b32_e32 v53, v241, v53, vcc
	v_cmp_lt_f32_e32 vcc, v54, v235
	s_nop 1
	v_cndmask_b32_e32 v54, v241, v54, vcc
	v_cmp_lt_f32_e32 vcc, v55, v235
	s_nop 1
	v_cndmask_b32_e32 v55, v241, v55, vcc
	v_cmp_lt_f32_e32 vcc, v56, v235
	s_nop 1
	v_cndmask_b32_e32 v56, v241, v56, vcc
	v_cmp_lt_f32_e32 vcc, v57, v235
	s_nop 1
	v_cndmask_b32_e32 v57, v241, v57, vcc
	v_cmp_lt_f32_e32 vcc, v58, v235
	s_nop 1
	v_cndmask_b32_e32 v58, v241, v58, vcc
	v_cmp_lt_f32_e32 vcc, v59, v235
	s_nop 1
	v_cndmask_b32_e32 v59, v241, v59, vcc
	v_cmp_lt_f32_e32 vcc, v60, v235
	s_nop 1
	v_cndmask_b32_e32 v60, v241, v60, vcc
	v_cmp_lt_f32_e32 vcc, v61, v235
	s_nop 1
	v_cndmask_b32_e32 v61, v241, v61, vcc
	v_cmp_lt_f32_e32 vcc, v62, v235
	s_nop 1
	v_cndmask_b32_e32 v62, v241, v62, vcc
	v_cmp_lt_f32_e32 vcc, v63, v235
	s_nop 1
	v_cndmask_b32_e32 v63, v241, v63, vcc
	v_cmp_lt_f32_e32 vcc, v64, v235
	s_nop 1
	v_cndmask_b32_e32 v64, v241, v64, vcc
	v_cmp_lt_f32_e32 vcc, v65, v235
	s_nop 1
	v_cndmask_b32_e32 v65, v241, v65, vcc
	v_cmp_lt_f32_e32 vcc, v2, v235
	s_nop 1
	v_cndmask_b32_e32 v2, v241, v2, vcc
	v_cmp_lt_f32_e32 vcc, v3, v235
	s_nop 1
	v_cndmask_b32_e32 v3, v241, v3, vcc
	v_cmp_lt_f32_e32 vcc, v4, v235
	s_nop 1
	v_cndmask_b32_e32 v4, v241, v4, vcc
	v_cmp_lt_f32_e32 vcc, v5, v235
	s_nop 1
	v_cndmask_b32_e32 v5, v241, v5, vcc
	v_cmp_lt_f32_e32 vcc, v6, v235
	s_nop 1
	v_cndmask_b32_e32 v6, v241, v6, vcc
	v_cmp_lt_f32_e32 vcc, v7, v235
	s_nop 1
	v_cndmask_b32_e32 v7, v241, v7, vcc
	v_cmp_lt_f32_e32 vcc, v8, v235
	s_nop 1
	v_cndmask_b32_e32 v8, v241, v8, vcc
	v_cmp_lt_f32_e32 vcc, v9, v235
	s_nop 1
	v_cndmask_b32_e32 v9, v241, v9, vcc
	v_cmp_lt_f32_e32 vcc, v10, v235
	s_nop 1
	v_cndmask_b32_e32 v10, v241, v10, vcc
	v_cmp_lt_f32_e32 vcc, v11, v235
	s_nop 1
	v_cndmask_b32_e32 v11, v241, v11, vcc
	v_cmp_lt_f32_e32 vcc, v12, v235
	s_nop 1
	v_cndmask_b32_e32 v12, v241, v12, vcc
	v_cmp_lt_f32_e32 vcc, v13, v235
	s_nop 1
	v_cndmask_b32_e32 v13, v241, v13, vcc
	v_cmp_lt_f32_e32 vcc, v14, v235
	s_nop 1
	v_cndmask_b32_e32 v14, v241, v14, vcc
	v_cmp_lt_f32_e32 vcc, v15, v235
	s_nop 1
	v_cndmask_b32_e32 v15, v241, v15, vcc
	v_cmp_lt_f32_e32 vcc, v16, v235
	s_nop 1
	v_cndmask_b32_e32 v16, v241, v16, vcc
	v_cmp_lt_f32_e32 vcc, v17, v235
	s_nop 1
	v_cndmask_b32_e32 v17, v241, v17, vcc

; #define LAS __attribute__((address_space(3)))
; template <int MODE  > ...
;     ...
;     {
;         LAS bf16_t* kb = (LAS bf16_t*)(lds + A_KBUF) + cur * 64 * KPITCH;
;         *(LAS u32x4*)(kb + skey * KPITCH + schunk * 8) = kreg;
;         if (NEEDV) { LAS bf16_t* vb = (LAS bf16_t*)(lds + A_VBUF) + cur * 64 * VPITCH;
;             *(LAS u32x4*)(vb + skey * VPITCH + schunk * 8) = vreg; }
;     }
;     __syncthreads();
;     for (;;) {
;         const bool has_next = rem != 0ull; int jn = 0;
;         if (has_next) { jn = 63 - __builtin_clzll(rem); rem &= ~(1ull << jn);
;             kreg = *(const u32x4*)(Kg + (size_t)(64 * jn + skey) * 128 + schunk * 8);
;             if (NEEDV) vreg = *(const u32x4*)(Vg + (size_t)(64 * jn + skey) * 128 + schunk * 8); }
;         const bool selbit = (MODE == 1) ? (((selmask >> j) & 1ull) != 0ull) : true;
;         bool active = true;
;         if (MODE == 1) active = __builtin_amdgcn_ballot_w64(selbit) != 0ull;
;         if (active) {
;             const LAS bf16_t* kb = (const LAS bf16_t*)(lds + A_KBUF) + cur * 64 * KPITCH;
;             constexpr int STEP = CMPM ? 16 : 1;
;             const int Bint = CMPM ? (1024 * j + 31 - t + 64 * h) : (64 * j - t + 4 * h);
;             const float sl = slope2 * (float)STEP;
;             const float mref = st.m; const bool fresh = !(mref > -1e28f);
;             const float mest = fresh ? 0.f : mref;
;             const float basef = selbit ? (slope2 * (float)Bint - mest) : -1e30f;
;             int ptype;
;             if (MODE == 1) ptype = (j == cblk) ? 1 : 0;
;             else if (MODE == 2) ptype = (j == cblk) ? 1 : ((j == cblk - 8) ? 2 : 0);
;             else ptype = (64 * j + 63 <= 4 * cblk - 2) ? 0 : 1;
;             f32x16 s0, s1;
;             { const float sl2 = sl + sl, sl3 = sl2 + sl;
; #pragma unroll
;               for (int g8 = 0; g8 < 4; ++g8) {
;                   const float b0 = __builtin_fmaf(sl, (float)(8 * g8), basef), b1 = __builtin_fmaf(sl, (float)(8 * g8 + 32), basef);
;                   s0[4 * g8] = b0; s0[4 * g8 + 1] = b0 + sl; s0[4 * g8 + 2] = b0 + sl2; s0[4 * g8 + 3] = b0 + sl3;
;                   s1[4 * g8] = b1; s1[4 * g8 + 1] = b1 + sl; s1[4 * g8 + 2] = b1 + sl2; s1[4 * g8 + 3] = b1 + sl3;
;               } }
;             if (ptype == 1) {
;                 const float thr = 0.5f * slope2 - mest;
; #pragma unroll
.Lm2_pre_w:
	s_waitcnt lgkmcnt(0)
	ds_write_b128 v165, v[220:223]
	ds_write_b128 v166, v[248:251] offset:18432
	s_waitcnt lgkmcnt(0)
	s_barrier
	v_mov_b32_e32 v224, 0
	v_mov_b32_e32 v225, v186
	v_mov_b32_e32 v252, v187
	v_mov_b32_e32 v253, v163
	v_readfirstlane_b32 s24, v142
	v_readfirstlane_b32 s25, v143
	v_readfirstlane_b32 s34, v140
	v_readfirstlane_b32 s35, v141
	v_lshlrev_b32_e32 v254, 4, v178
	v_and_b32_e32 v254, 0x70, v254
	v_lshl_or_b32 v254, v161, 8, v254
.LBB0_268:
	s_mov_b32 s19, 0
	s_cmp_eq_u64 s[16:17], 0
	s_cbranch_scc1 .Lm20_noload
	s_flbit_i32_b64 s4, s[16:17]
	s_xor_b32 s4, s4, 63
	s_lshl_b64 vcc, 1, s4
	s_andn2_b64 s[16:17], s[16:17], vcc
	s_mov_b32 s19, 1
	v_lshl_add_u32 v34, s4, 14, v254
	global_load_dwordx4 v[130:133], v34, s[24:25]
	global_load_dwordx4 v[134:137], v34, s[34:35]
.Lm20_noload:
.Lm2_body0:
	ds_read_b128 v[66:69], v188
	ds_read_b128 v[70:73], v188 offset:4608
	ds_read_b128 v[74:77], v188 offset:32
	ds_read_b128 v[78:81], v188 offset:4640
	ds_read_b128 v[82:85], v188 offset:64
	ds_read_b128 v[86:89], v188 offset:4672
	ds_read_b128 v[90:93], v188 offset:96
	ds_read_b128 v[94:97], v188 offset:4704
	v_lshl_add_u32 v1, s20, 6, v167
	v_cvt_f32_i32_e32 v50, v1
	v_cmp_nlt_f32_e64 s[14:15], s71, v192
	s_cmp_eq_u32 s20, s23
	s_cselect_b32 s21, 2, 0
	s_cmp_lg_u32 s20, s83
	s_cselect_b32 s68, s21, 1
	s_cmp_eq_u32 s68, 0
	v_cndmask_b32_e64 v1, v192, 0, s[14:15]
	v_fma_f32 v62, v186, v50, -v1
	v_fma_f32 v34, 0, v186, v62
	v_fmamk_f32 v38, v186, 0x41000000, v62
	v_fmamk_f32 v42, v186, 0x41800000, v62
	v_fmamk_f32 v46, v186, 0x41c00000, v62
	v_fmamk_f32 v50, v186, 0x42000000, v62
	v_fmamk_f32 v54, v186, 0x42200000, v62
	v_fmamk_f32 v58, v186, 0x42400000, v62
	v_fmac_f32_e32 v62, 0x42600000, v186
	v_pk_add_f32 v[36:37], v[252:253], v[34:35] op_sel_hi:[1,0]
	v_pk_add_f32 v[34:35], v[224:225], v[34:35] op_sel_hi:[1,0]
	v_pk_add_f32 v[40:41], v[252:253], v[38:39] op_sel_hi:[1,0]
	v_pk_add_f32 v[38:39], v[224:225], v[38:39] op_sel_hi:[1,0]
	v_pk_add_f32 v[44:45], v[252:253], v[42:43] op_sel_hi:[1,0]
	v_pk_add_f32 v[42:43], v[224:225], v[42:43] op_sel_hi:[1,0]
	v_pk_add_f32 v[48:49], v[252:253], v[46:47] op_sel_hi:[1,0]
	v_pk_add_f32 v[46:47], v[224:225], v[46:47] op_sel_hi:[1,0]
	v_pk_add_f32 v[52:53], v[252:253], v[50:51] op_sel_hi:[1,0]
	v_pk_add_f32 v[50:51], v[224:225], v[50:51] op_sel_hi:[1,0]
	v_pk_add_f32 v[56:57], v[252:253], v[54:55] op_sel_hi:[1,0]
	v_pk_add_f32 v[54:55], v[224:225], v[54:55] op_sel_hi:[1,0]
	v_pk_add_f32 v[60:61], v[252:253], v[58:59] op_sel_hi:[1,0]
	v_pk_add_f32 v[58:59], v[224:225], v[58:59] op_sel_hi:[1,0]
	v_pk_add_f32 v[64:65], v[252:253], v[62:63] op_sel_hi:[1,0]
	v_pk_add_f32 v[62:63], v[224:225], v[62:63] op_sel_hi:[1,0]
	s_cbranch_scc1 .Lm20_qk
	s_cmp_eq_u32 s68, 1
	s_cbranch_scc1 .Lm20_edge1
	v_sub_f32_e32 v235, v162, v1
	v_cmp_gt_f32_e32 vcc, v34, v235
	s_nop 1
	v_cndmask_b32_e32 v34, v241, v34, vcc
	v_cmp_gt_f32_e32 vcc, v35, v235
	s_nop 1
	v_cndmask_b32_e32 v35, v241, v35, vcc
	v_cmp_gt_f32_e32 vcc, v36, v235
	s_nop 1
	v_cndmask_b32_e32 v36, v241, v36, vcc
	v_cmp_gt_f32_e32 vcc, v37, v235
	s_nop 1
	v_cndmask_b32_e32 v37, v241, v37, vcc
	v_cmp_gt_f32_e32 vcc, v38, v235
	s_nop 1
	v_cndmask_b32_e32 v38, v241, v38, vcc
	v_cmp_gt_f32_e32 vcc, v39, v235
	s_nop 1
	v_cndmask_b32_e32 v39, v241, v39, vcc
	v_cmp_gt_f32_e32 vcc, v40, v235
	s_nop 1
	v_cndmask_b32_e32 v40, v241, v40, vcc
	v_cmp_gt_f32_e32 vcc, v41, v235
	s_nop 1
	v_cndmask_b32_e32 v41, v241, v41, vcc
	v_cmp_gt_f32_e32 vcc, v42, v235
	s_nop 1
	v_cndmask_b32_e32 v42, v241, v42, vcc
	v_cmp_gt_f32_e32 vcc, v43, v235
	s_nop 1
	v_cndmask_b32_e32 v43, v241, v43, vcc
	v_cmp_gt_f32_e32 vcc, v44, v235
	s_nop 1
	v_cndmask_b32_e32 v44, v241, v44, vcc
	v_cmp_gt_f32_e32 vcc, v45, v235
	s_nop 1
	v_cndmask_b32_e32 v45, v241, v45, vcc
	v_cmp_gt_f32_e32 vcc, v46, v235
	s_nop 1
	v_cndmask_b32_e32 v46, v241, v46, vcc
	v_cmp_gt_f32_e32 vcc, v47, v235
	s_nop 1
	v_cndmask_b32_e32 v47, v241, v47, vcc
	v_cmp_gt_f32_e32 vcc, v48, v235
	s_nop 1
	v_cndmask_b32_e32 v48, v241, v48, vcc
	v_cmp_gt_f32_e32 vcc, v49, v235
	s_nop 1
	v_cndmask_b32_e32 v49, v241, v49, vcc
	v_cmp_gt_f32_e32 vcc, v50, v235
	s_nop 1
	v_cndmask_b32_e32 v50, v241, v50, vcc
	v_cmp_gt_f32_e32 vcc, v51, v235
	s_nop 1
	v_cndmask_b32_e32 v51, v241, v51, vcc
	v_cmp_gt_f32_e32 vcc, v52, v235
	s_nop 1
	v_cndmask_b32_e32 v52, v241, v52, vcc
	v_cmp_gt_f32_e32 vcc, v53, v235
	s_nop 1
	v_cndmask_b32_e32 v53, v241, v53, vcc
	v_cmp_gt_f32_e32 vcc, v54, v235
	s_nop 1
	v_cndmask_b32_e32 v54, v241, v54, vcc
	v_cmp_gt_f32_e32 vcc, v55, v235
	s_nop 1
	v_cndmask_b32_e32 v55, v241, v55, vcc
	v_cmp_gt_f32_e32 vcc, v56, v235
	s_nop 1
	v_cndmask_b32_e32 v56, v241, v56, vcc
	v_cmp_gt_f32_e32 vcc, v57, v235
	s_nop 1
	v_cndmask_b32_e32 v57, v241, v57, vcc
	v_cmp_gt_f32_e32 vcc, v58, v235
	s_nop 1
	v_cndmask_b32_e32 v58, v241, v58, vcc
	v_cmp_gt_f32_e32 vcc, v59, v235
	s_nop 1
	v_cndmask_b32_e32 v59, v241, v59, vcc
	v_cmp_gt_f32_e32 vcc, v60, v235
	s_nop 1
	v_cndmask_b32_e32 v60, v241, v60, vcc
	v_cmp_gt_f32_e32 vcc, v61, v235
	s_nop 1
	v_cndmask_b32_e32 v61, v241, v61, vcc
	v_cmp_gt_f32_e32 vcc, v62, v235
	s_nop 1
	v_cndmask_b32_e32 v62, v241, v62, vcc
	v_cmp_gt_f32_e32 vcc, v63, v235
	s_nop 1
	v_cndmask_b32_e32 v63, v241, v63, vcc
	v_cmp_gt_f32_e32 vcc, v64, v235
	s_nop 1
	v_cndmask_b32_e32 v64, v241, v64, vcc
	v_cmp_gt_f32_e32 vcc, v65, v235
	s_nop 1
	v_cndmask_b32_e32 v65, v241, v65, vcc
	s_branch .Lm20_qk
; template <int MODE  > ...
;     ...
;             if (ptype == 1) {
;                 const float thr = 0.5f * slope2 - mest;
; #pragma unroll
;                 for (int i = 0; i < 16; ++i) { s0[i] = (s0[i] < thr) ? s0[i] : -1e30f; s1[i] = (s1[i] < thr) ? s1[i] : -1e30f; }
.Lm20_edge1:
	v_sub_f32_e32 v235, v189, v1
	v_cmp_lt_f32_e32 vcc, v34, v235
	s_nop 1
	v_cndmask_b32_e32 v34, v241, v34, vcc
	v_cmp_lt_f32_e32 vcc, v35, v235
	s_nop 1
	v_cndmask_b32_e32 v35, v241, v35, vcc
	v_cmp_lt_f32_e32 vcc, v36, v235
	s_nop 1
	v_cndmask_b32_e32 v36, v241, v36, vcc
	v_cmp_lt_f32_e32 vcc, v37, v235
	s_nop 1
	v_cndmask_b32_e32 v37, v241, v37, vcc
	v_cmp_lt_f32_e32 vcc, v38, v235
	s_nop 1
	v_cndmask_b32_e32 v38, v241, v38, vcc
	v_cmp_lt_f32_e32 vcc, v39, v235
	s_nop 1
	v_cndmask_b32_e32 v39, v241, v39, vcc
	v_cmp_lt_f32_e32 vcc, v40, v235
	s_nop 1
	v_cndmask_b32_e32 v40, v241, v40, vcc
	v_cmp_lt_f32_e32 vcc, v41, v235
	s_nop 1
	v_cndmask_b32_e32 v41, v241, v41, vcc
	v_cmp_lt_f32_e32 vcc, v42, v235
	s_nop 1
	v_cndmask_b32_e32 v42, v241, v42, vcc
	v_cmp_lt_f32_e32 vcc, v43, v235
	s_nop 1
	v_cndmask_b32_e32 v43, v241, v43, vcc
	v_cmp_lt_f32_e32 vcc, v44, v235
	s_nop 1
	v_cndmask_b32_e32 v44, v241, v44, vcc
	v_cmp_lt_f32_e32 vcc, v45, v235
	s_nop 1
	v_cndmask_b32_e32 v45, v241, v45, vcc
	v_cmp_lt_f32_e32 vcc, v46, v235
	s_nop 1
	v_cndmask_b32_e32 v46, v241, v46, vcc
	v_cmp_lt_f32_e32 vcc, v47, v235
	s_nop 1
	v_cndmask_b32_e32 v47, v241, v47, vcc
	v_cmp_lt_f32_e32 vcc, v48, v235
	s_nop 1
	v_cndmask_b32_e32 v48, v241, v48, vcc
	v_cmp_lt_f32_e32 vcc, v49, v235
	s_nop 1
	v_cndmask_b32_e32 v49, v241, v49, vcc
	v_cmp_lt_f32_e32 vcc, v50, v235
	s_nop 1
	v_cndmask_b32_e32 v50, v241, v50, vcc
	v_cmp_lt_f32_e32 vcc, v51, v235
	s_nop 1
	v_cndmask_b32_e32 v51, v241, v51, vcc
	v_cmp_lt_f32_e32 vcc, v52, v235
	s_nop 1
	v_cndmask_b32_e32 v52, v241, v52, vcc
	v_cmp_lt_f32_e32 vcc, v53, v235
	s_nop 1
	v_cndmask_b32_e32 v53, v241, v53, vcc
	v_cmp_lt_f32_e32 vcc, v54, v235
	s_nop 1
	v_cndmask_b32_e32 v54, v241, v54, vcc
	v_cmp_lt_f32_e32 vcc, v55, v235
	s_nop 1
	v_cndmask_b32_e32 v55, v241, v55, vcc
	v_cmp_lt_f32_e32 vcc, v56, v235
	s_nop 1
	v_cndmask_b32_e32 v56, v241, v56, vcc
	v_cmp_lt_f32_e32 vcc, v57, v235
	s_nop 1
	v_cndmask_b32_e32 v57, v241, v57, vcc
	v_cmp_lt_f32_e32 vcc, v58, v235
	s_nop 1
	v_cndmask_b32_e32 v58, v241, v58, vcc
	v_cmp_lt_f32_e32 vcc, v59, v235
	s_nop 1
	v_cndmask_b32_e32 v59, v241, v59, vcc
	v_cmp_lt_f32_e32 vcc, v60, v235
	s_nop 1
	v_cndmask_b32_e32 v60, v241, v60, vcc
	v_cmp_lt_f32_e32 vcc, v61, v235
	s_nop 1
	v_cndmask_b32_e32 v61, v241, v61, vcc
	v_cmp_lt_f32_e32 vcc, v62, v235
	s_nop 1
	v_cndmask_b32_e32 v62, v241, v62, vcc
	v_cmp_lt_f32_e32 vcc, v63, v235
	s_nop 1
	v_cndmask_b32_e32 v63, v241, v63, vcc
	v_cmp_lt_f32_e32 vcc, v64, v235
	s_nop 1
	v_cndmask_b32_e32 v64, v241, v64, vcc
	v_cmp_lt_f32_e32 vcc, v65, v235
	s_nop 1
	v_cndmask_b32_e32 v65, v241, v65, vcc

; #define LAS __attribute__((address_space(3)))
; template <int MODE  > ...
;     ...
;         const bool has_next = rem != 0ull; int jn = 0;
;         if (has_next) { jn = 63 - __builtin_clzll(rem); rem &= ~(1ull << jn);
;             kreg = *(const u32x4*)(Kg + (size_t)(64 * jn + skey) * 128 + schunk * 8);
;             if (NEEDV) vreg = *(const u32x4*)(Vg + (size_t)(64 * jn + skey) * 128 + schunk * 8); }
;         const bool selbit = (MODE == 1) ? (((selmask >> j) & 1ull) != 0ull) : true;
;         bool active = true;
;         if (MODE == 1) active = __builtin_amdgcn_ballot_w64(selbit) != 0ull;
;         if (active) {
;             const LAS bf16_t* kb = (const LAS bf16_t*)(lds + A_KBUF) + cur * 64 * KPITCH;
;             constexpr int STEP = CMPM ? 16 : 1;
;             const int Bint = CMPM ? (1024 * j + 31 - t + 64 * h) : (64 * j - t + 4 * h);
;             const float sl = slope2 * (float)STEP;
;             const float mref = st.m; const bool fresh = !(mref > -1e28f);
;             const float mest = fresh ? 0.f : mref;
;             const float basef = selbit ? (slope2 * (float)Bint - mest) : -1e30f;
;             int ptype;
;             if (MODE == 1) ptype = (j == cblk) ? 1 : 0;
;             else if (MODE == 2) ptype = (j == cblk) ? 1 : ((j == cblk - 8) ? 2 : 0);
;             else ptype = (64 * j + 63 <= 4 * cblk - 2) ? 0 : 1;
;             f32x16 s0, s1;
;             { const float sl2 = sl + sl, sl3 = sl2 + sl;
; #pragma unroll
;               for (int g8 = 0; g8 < 4; ++g8) {
;                   const float b0 = __builtin_fmaf(sl, (float)(8 * g8), basef), b1 = __builtin_fmaf(sl, (float)(8 * g8 + 32), basef);
;                   s0[4 * g8] = b0; s0[4 * g8 + 1] = b0 + sl; s0[4 * g8 + 2] = b0 + sl2; s0[4 * g8 + 3] = b0 + sl3;
;                   s1[4 * g8] = b1; s1[4 * g8 + 1] = b1 + sl; s1[4 * g8 + 2] = b1 + sl2; s1[4 * g8 + 3] = b1 + sl3;
;               } }
;             if (ptype == 1) {
;                 const float thr = 0.5f * slope2 - mest;
; #pragma unroll
;                 for (int i = 0; i < 16; ++i) { s0[i] = (s0[i] < thr) ? s0[i] : -1e30f; s1[i] = (s1[i] < thr) ? s1[i] : -1e30f; }
;             } else if (ptype == 2) {
;                 const float thr = -511.5f * slope2 - mest;
; #pragma unroll
;                 for (int i = 0; i < 16; ++i) { s0[i] = (s0[i] > thr) ? s0[i] : -1e30f; s1[i] = (s1[i] > thr) ? s1[i] : -1e30f; }
;             }
.Lm2_loop1:
	s_mov_b32 s19, 0
	s_cmp_eq_u64 s[16:17], 0
	s_cbranch_scc1 .Lm21_noload
	s_flbit_i32_b64 s4, s[16:17]
	s_xor_b32 s4, s4, 63
	s_lshl_b64 vcc, 1, s4
	s_andn2_b64 s[16:17], s[16:17], vcc
	s_mov_b32 s19, 1
	v_lshl_add_u32 v34, s4, 14, v254
	global_load_dwordx4 v[226:229], v34, s[24:25]
	global_load_dwordx4 v[230:233], v34, s[34:35]
.Lm21_noload:
.Lm2_body1:
	ds_read_b128 v[66:69], v188 offset:9216
	ds_read_b128 v[70:73], v188 offset:13824
	ds_read_b128 v[74:77], v188 offset:9248
	ds_read_b128 v[78:81], v188 offset:13856
	ds_read_b128 v[82:85], v188 offset:9280
	ds_read_b128 v[86:89], v188 offset:13888
	ds_read_b128 v[90:93], v188 offset:9312
	ds_read_b128 v[94:97], v188 offset:13920
	v_lshl_add_u32 v1, s20, 6, v167
	v_cvt_f32_i32_e32 v50, v1
	v_cmp_nlt_f32_e64 s[14:15], s71, v192
	s_cmp_eq_u32 s20, s23
	s_cselect_b32 s21, 2, 0
	s_cmp_lg_u32 s20, s83
	s_cselect_b32 s68, s21, 1
	s_cmp_eq_u32 s68, 0
	v_cndmask_b32_e64 v1, v192, 0, s[14:15]
	v_fma_f32 v62, v186, v50, -v1
	v_fma_f32 v34, 0, v186, v62
	v_fmamk_f32 v38, v186, 0x41000000, v62
	v_fmamk_f32 v42, v186, 0x41800000, v62
	v_fmamk_f32 v46, v186, 0x41c00000, v62
	v_fmamk_f32 v50, v186, 0x42000000, v62
	v_fmamk_f32 v54, v186, 0x42200000, v62
	v_fmamk_f32 v58, v186, 0x42400000, v62
	v_fmac_f32_e32 v62, 0x42600000, v186
	v_pk_add_f32 v[36:37], v[252:253], v[34:35] op_sel_hi:[1,0]
	v_pk_add_f32 v[34:35], v[224:225], v[34:35] op_sel_hi:[1,0]
	v_pk_add_f32 v[40:41], v[252:253], v[38:39] op_sel_hi:[1,0]
	v_pk_add_f32 v[38:39], v[224:225], v[38:39] op_sel_hi:[1,0]
	v_pk_add_f32 v[44:45], v[252:253], v[42:43] op_sel_hi:[1,0]
	v_pk_add_f32 v[42:43], v[224:225], v[42:43] op_sel_hi:[1,0]
	v_pk_add_f32 v[48:49], v[252:253], v[46:47] op_sel_hi:[1,0]
	v_pk_add_f32 v[46:47], v[224:225], v[46:47] op_sel_hi:[1,0]
	v_pk_add_f32 v[52:53], v[252:253], v[50:51] op_sel_hi:[1,0]
	v_pk_add_f32 v[50:51], v[224:225], v[50:51] op_sel_hi:[1,0]
	v_pk_add_f32 v[56:57], v[252:253], v[54:55] op_sel_hi:[1,0]
	v_pk_add_f32 v[54:55], v[224:225], v[54:55] op_sel_hi:[1,0]
	v_pk_add_f32 v[60:61], v[252:253], v[58:59] op_sel_hi:[1,0]
	v_pk_add_f32 v[58:59], v[224:225], v[58:59] op_sel_hi:[1,0]
	v_pk_add_f32 v[64:65], v[252:253], v[62:63] op_sel_hi:[1,0]
	v_pk_add_f32 v[62:63], v[224:225], v[62:63] op_sel_hi:[1,0]
	s_cbranch_scc1 .Lm21_qk
	s_cmp_eq_u32 s68, 1
	s_cbranch_scc1 .Lm21_edge1
	v_sub_f32_e32 v235, v162, v1
	v_cmp_gt_f32_e32 vcc, v34, v235
	s_nop 1
	v_cndmask_b32_e32 v34, v241, v34, vcc
	v_cmp_gt_f32_e32 vcc, v35, v235
	s_nop 1
	v_cndmask_b32_e32 v35, v241, v35, vcc
	v_cmp_gt_f32_e32 vcc, v36, v235
	s_nop 1
	v_cndmask_b32_e32 v36, v241, v36, vcc
	v_cmp_gt_f32_e32 vcc, v37, v235
	s_nop 1
	v_cndmask_b32_e32 v37, v241, v37, vcc
	v_cmp_gt_f32_e32 vcc, v38, v235
	s_nop 1
	v_cndmask_b32_e32 v38, v241, v38, vcc
	v_cmp_gt_f32_e32 vcc, v39, v235
	s_nop 1
	v_cndmask_b32_e32 v39, v241, v39, vcc
	v_cmp_gt_f32_e32 vcc, v40, v235
	s_nop 1
	v_cndmask_b32_e32 v40, v241, v40, vcc
	v_cmp_gt_f32_e32 vcc, v41, v235
	s_nop 1
	v_cndmask_b32_e32 v41, v241, v41, vcc
	v_cmp_gt_f32_e32 vcc, v42, v235
	s_nop 1
	v_cndmask_b32_e32 v42, v241, v42, vcc
	v_cmp_gt_f32_e32 vcc, v43, v235
	s_nop 1
	v_cndmask_b32_e32 v43, v241, v43, vcc
	v_cmp_gt_f32_e32 vcc, v44, v235
	s_nop 1
	v_cndmask_b32_e32 v44, v241, v44, vcc
	v_cmp_gt_f32_e32 vcc, v45, v235
	s_nop 1
	v_cndmask_b32_e32 v45, v241, v45, vcc
	v_cmp_gt_f32_e32 vcc, v46, v235
	s_nop 1
	v_cndmask_b32_e32 v46, v241, v46, vcc
	v_cmp_gt_f32_e32 vcc, v47, v235
	s_nop 1
	v_cndmask_b32_e32 v47, v241, v47, vcc
	v_cmp_gt_f32_e32 vcc, v48, v235
	s_nop 1
	v_cndmask_b32_e32 v48, v241, v48, vcc
	v_cmp_gt_f32_e32 vcc, v49, v235
	s_nop 1
	v_cndmask_b32_e32 v49, v241, v49, vcc
	v_cmp_gt_f32_e32 vcc, v50, v235
	s_nop 1
	v_cndmask_b32_e32 v50, v241, v50, vcc
	v_cmp_gt_f32_e32 vcc, v51, v235
	s_nop 1
	v_cndmask_b32_e32 v51, v241, v51, vcc
	v_cmp_gt_f32_e32 vcc, v52, v235
	s_nop 1
	v_cndmask_b32_e32 v52, v241, v52, vcc
	v_cmp_gt_f32_e32 vcc, v53, v235
	s_nop 1
	v_cndmask_b32_e32 v53, v241, v53, vcc
	v_cmp_gt_f32_e32 vcc, v54, v235
	s_nop 1
	v_cndmask_b32_e32 v54, v241, v54, vcc
	v_cmp_gt_f32_e32 vcc, v55, v235
	s_nop 1
	v_cndmask_b32_e32 v55, v241, v55, vcc
	v_cmp_gt_f32_e32 vcc, v56, v235
	s_nop 1
	v_cndmask_b32_e32 v56, v241, v56, vcc
	v_cmp_gt_f32_e32 vcc, v57, v235
	s_nop 1
	v_cndmask_b32_e32 v57, v241, v57, vcc
	v_cmp_gt_f32_e32 vcc, v58, v235
	s_nop 1
	v_cndmask_b32_e32 v58, v241, v58, vcc
	v_cmp_gt_f32_e32 vcc, v59, v235
	s_nop 1
	v_cndmask_b32_e32 v59, v241, v59, vcc
	v_cmp_gt_f32_e32 vcc, v60, v235
	s_nop 1
	v_cndmask_b32_e32 v60, v241, v60, vcc
	v_cmp_gt_f32_e32 vcc, v61, v235
	s_nop 1
	v_cndmask_b32_e32 v61, v241, v61, vcc
	v_cmp_gt_f32_e32 vcc, v62, v235
	s_nop 1
	v_cndmask_b32_e32 v62, v241, v62, vcc
	v_cmp_gt_f32_e32 vcc, v63, v235
	s_nop 1
	v_cndmask_b32_e32 v63, v241, v63, vcc
	v_cmp_gt_f32_e32 vcc, v64, v235
	s_nop 1
	v_cndmask_b32_e32 v64, v241, v64, vcc
	v_cmp_gt_f32_e32 vcc, v65, v235
	s_nop 1
	v_cndmask_b32_e32 v65, v241, v65, vcc
	s_branch .Lm21_qk
